# v40: v34 + the two wave halves keep their one-segment offset through the epilogue of every tile but the last (alignment and re-offset barriers only around the last tile) in both input-projection GEMMs
# baseline (speedup 1.0000x reference)
.Lb1w4_j:
	s_waitcnt lgkmcnt(0)
	s_barrier
	s_setprio 1
	s_waitcnt lgkmcnt(0)
	v_mfma_f32_16x16x32_bf16 v[64:67], v[132:135], v[184:187], v[64:67]
	v_mfma_f32_16x16x32_bf16 v[60:63], v[156:159], v[184:187], v[60:63]
	v_mfma_f32_16x16x32_bf16 v[48:51], v[132:135], v[192:195], v[48:51]
	v_mfma_f32_16x16x32_bf16 v[44:47], v[156:159], v[192:195], v[44:47]
	v_mfma_f32_16x16x32_bf16 v[32:35], v[132:135], v[200:203], v[32:35]
	v_mfma_f32_16x16x32_bf16 v[28:31], v[156:159], v[200:203], v[28:31]
	v_mfma_f32_16x16x32_bf16 v[16:19], v[132:135], v[208:211], v[16:19]
	v_mfma_f32_16x16x32_bf16 v[12:15], v[156:159], v[208:211], v[12:15]
	v_mfma_f32_16x16x32_bf16 v[64:67], v[152:155], v[188:191], v[64:67]
	v_mfma_f32_16x16x32_bf16 v[60:63], v[160:163], v[188:191], v[60:63]
	v_mfma_f32_16x16x32_bf16 v[48:51], v[152:155], v[196:199], v[48:51]
	v_mfma_f32_16x16x32_bf16 v[44:47], v[160:163], v[196:199], v[44:47]
	v_mfma_f32_16x16x32_bf16 v[32:35], v[152:155], v[204:207], v[32:35]
	v_mfma_f32_16x16x32_bf16 v[28:31], v[160:163], v[204:207], v[28:31]
	v_mfma_f32_16x16x32_bf16 v[16:19], v[152:155], v[212:215], v[16:19]
	v_mfma_f32_16x16x32_bf16 v[12:15], v[160:163], v[212:215], v[12:15]
	s_setprio 0
	s_setprio 1
	v_mfma_f32_16x16x32_bf16 v[56:59], v[164:167], v[184:187], v[56:59]
	v_mfma_f32_16x16x32_bf16 v[52:55], v[172:175], v[184:187], v[52:55]
	v_mfma_f32_16x16x32_bf16 v[40:43], v[164:167], v[192:195], v[40:43]
	v_mfma_f32_16x16x32_bf16 v[36:39], v[172:175], v[192:195], v[36:39]
	v_mfma_f32_16x16x32_bf16 v[24:27], v[164:167], v[200:203], v[24:27]
	v_mfma_f32_16x16x32_bf16 v[20:23], v[172:175], v[200:203], v[20:23]
	v_mfma_f32_16x16x32_bf16 v[8:11], v[164:167], v[208:211], v[8:11]
	v_mfma_f32_16x16x32_bf16 v[4:7], v[172:175], v[208:211], v[4:7]
	v_mfma_f32_16x16x32_bf16 v[56:59], v[168:171], v[188:191], v[56:59]
	v_mfma_f32_16x16x32_bf16 v[52:55], v[180:183], v[188:191], v[52:55]
	v_mfma_f32_16x16x32_bf16 v[40:43], v[168:171], v[196:199], v[40:43]
	v_mfma_f32_16x16x32_bf16 v[36:39], v[180:183], v[196:199], v[36:39]
	v_mfma_f32_16x16x32_bf16 v[24:27], v[168:171], v[204:207], v[24:27]
	v_mfma_f32_16x16x32_bf16 v[20:23], v[180:183], v[204:207], v[20:23]
	v_mfma_f32_16x16x32_bf16 v[8:11], v[168:171], v[212:215], v[8:11]
	v_mfma_f32_16x16x32_bf16 v[4:7], v[180:183], v[212:215], v[4:7]
	s_setprio 0
	s_barrier
	s_add_i32 s49, s49, 2
	s_add_u32 s0, s0, 0x100
	s_addc_u32 s1, s1, 0
	s_add_u32 s29, s29, 0x100
	s_addc_u32 s42, s42, 0
	s_cmp_gt_u32 s49, 13
	s_cbranch_scc0 .LBB0_156
	s_and_b64 vcc, exec, s[18:19]
	s_cbranch_vccz .LBB0_159
	s_and_b64 vcc, exec, s[4:5]
	s_cbranch_vccnz .LBB0_159
	s_barrier

.LBB0_252:
	s_andn2_b64 vcc, exec, s[12:13]
	s_cbranch_vccnz .LBB0_151
	s_branch .LBB0_151

.La1w4_j:
	s_waitcnt lgkmcnt(0)
	s_barrier
	s_setprio 1
	s_waitcnt lgkmcnt(0)
	v_mfma_f32_16x16x32_bf16 v[64:67], v[142:145], v[178:181], v[64:67]
	v_mfma_f32_16x16x32_bf16 v[56:59], v[150:153], v[178:181], v[56:59]
	v_mfma_f32_16x16x32_bf16 v[48:51], v[142:145], v[186:189], v[48:51]
	v_mfma_f32_16x16x32_bf16 v[40:43], v[150:153], v[186:189], v[40:43]
	v_mfma_f32_16x16x32_bf16 v[32:35], v[142:145], v[194:197], v[32:35]
	v_mfma_f32_16x16x32_bf16 v[24:27], v[150:153], v[194:197], v[24:27]
	v_mfma_f32_16x16x32_bf16 v[16:19], v[142:145], v[202:205], v[16:19]
	v_mfma_f32_16x16x32_bf16 v[8:11], v[150:153], v[202:205], v[8:11]
	v_mfma_f32_16x16x32_bf16 v[64:67], v[146:149], v[182:185], v[64:67]
	v_mfma_f32_16x16x32_bf16 v[56:59], v[154:157], v[182:185], v[56:59]
	v_mfma_f32_16x16x32_bf16 v[48:51], v[146:149], v[190:193], v[48:51]
	v_mfma_f32_16x16x32_bf16 v[40:43], v[154:157], v[190:193], v[40:43]
	v_mfma_f32_16x16x32_bf16 v[32:35], v[146:149], v[198:201], v[32:35]
	v_mfma_f32_16x16x32_bf16 v[24:27], v[154:157], v[198:201], v[24:27]
	v_mfma_f32_16x16x32_bf16 v[16:19], v[146:149], v[206:209], v[16:19]
	v_mfma_f32_16x16x32_bf16 v[8:11], v[154:157], v[206:209], v[8:11]
	s_setprio 0
	s_setprio 1
	v_mfma_f32_16x16x32_bf16 v[60:63], v[158:161], v[178:181], v[60:63]
	v_mfma_f32_16x16x32_bf16 v[52:55], v[166:169], v[178:181], v[52:55]
	v_mfma_f32_16x16x32_bf16 v[44:47], v[158:161], v[186:189], v[44:47]
	v_mfma_f32_16x16x32_bf16 v[36:39], v[166:169], v[186:189], v[36:39]
	v_mfma_f32_16x16x32_bf16 v[28:31], v[158:161], v[194:197], v[28:31]
	v_mfma_f32_16x16x32_bf16 v[20:23], v[166:169], v[194:197], v[20:23]
	v_mfma_f32_16x16x32_bf16 v[12:15], v[158:161], v[202:205], v[12:15]
	v_mfma_f32_16x16x32_bf16 v[4:7], v[166:169], v[202:205], v[4:7]
	v_mfma_f32_16x16x32_bf16 v[60:63], v[162:165], v[182:185], v[60:63]
	v_mfma_f32_16x16x32_bf16 v[52:55], v[170:173], v[182:185], v[52:55]
	v_mfma_f32_16x16x32_bf16 v[44:47], v[162:165], v[190:193], v[44:47]
	v_mfma_f32_16x16x32_bf16 v[36:39], v[170:173], v[190:193], v[36:39]
	v_mfma_f32_16x16x32_bf16 v[28:31], v[162:165], v[198:201], v[28:31]
	v_mfma_f32_16x16x32_bf16 v[20:23], v[170:173], v[198:201], v[20:23]
	v_mfma_f32_16x16x32_bf16 v[12:15], v[162:165], v[206:209], v[12:15]
	v_mfma_f32_16x16x32_bf16 v[4:7], v[170:173], v[206:209], v[4:7]
	s_setprio 0
	s_barrier
	s_add_i32 s51, s51, 2
	s_add_u32 s0, s0, 0x100
	s_addc_u32 s1, s1, 0
	s_add_u32 s49, s49, 0x100
	s_addc_u32 s50, s50, 0
	s_cmp_gt_u32 s51, 13
	s_cbranch_scc0 .LBB0_446
	s_and_b64 vcc, exec, s[18:19]
	s_cbranch_vccz .LBB0_449
	s_and_b64 vcc, exec, s[6:7]
	s_cbranch_vccnz .LBB0_449
	s_barrier

.LBB0_470:
	s_andn2_b64 vcc, exec, s[8:9]
	s_cbranch_vccnz .LBB0_441
	s_branch .LBB0_441
